# P1 epilogue head-norm reduction: two dependent ds_bpermute round trips per row replaced by permlane16/32 swaps (VALU only), on top of v40
# speedup vs baseline: 1.0013x; 1.0013x over previous
.LBB0_510:
	s_and_b64 s[70:71], s[8:9], s[4:5]
	s_ashr_i32 s4, s76, 11
	s_mul_i32 s4, s65, s4
	s_add_i32 s4, s4, s63
	s_ashr_i32 s5, s4, 31
	v_lshl_add_u64 v[180:181], v[178:179], 0, v[152:153]
	s_lshl_b64 s[4:5], s[4:5], 18
	v_cndmask_b32_e64 v0, 0, 1, s[74:75]
	v_lshl_add_u64 v[182:183], v[180:181], 0, s[4:5]
	s_andn2_b64 vcc, exec, s[10:11]
	v_cmp_ne_u32_e64 s[10:11], 1, v0
	s_cbranch_vccnz .LBB0_517
	s_and_b64 vcc, exec, s[10:11]
	s_cbranch_vccnz .LBB0_632
	v_mul_f32_e32 v4, v17, v17
	v_fmac_f32_e32 v4, v16, v16
	v_fmac_f32_e32 v4, v18, v18
	v_fmac_f32_e32 v4, v19, v19
	v_fmac_f32_e32 v4, v20, v20
	v_fmac_f32_e32 v4, v21, v21
	v_fmac_f32_e32 v4, v22, v22
	v_fmac_f32_e32 v4, v23, v23
	v_pk_mul_f32 v[2:3], v[24:25], v[24:25]
	v_pk_mul_f32 v[0:1], v[26:27], v[26:27]
	v_add_f32_e32 v2, v2, v4
	v_add_f32_e32 v2, v3, v2
	v_add_f32_e32 v0, v0, v2
	v_add_f32_e32 v4, v1, v0
	v_pk_mul_f32 v[2:3], v[28:29], v[28:29]
	v_pk_mul_f32 v[0:1], v[30:31], v[30:31]
	v_add_f32_e32 v2, v2, v4
	v_add_f32_e32 v2, v3, v2
	v_add_f32_e32 v0, v0, v2
	v_add_f32_e32 v0, v1, v0
	v_mov_b32_e32 v1, v0
	s_nop 1
	v_permlane16_swap_b32_e32 v1, v0
	v_add_f32_e32 v0, v0, v1
	v_mov_b32_e32 v1, v0
	s_nop 1
	v_permlane32_swap_b32_e32 v1, v0
	v_add_f32_e32 v0, v0, v1
	s_waitcnt vmcnt(0)
	v_mul_f32_e32 v1, v150, v150
	v_mul_f32_e32 v0, v1, v0
	v_fmamk_f32 v0, v0, 0x3c800000, v194
	v_mul_f32_e32 v1, 0x4b800000, v0
	v_cmp_gt_f32_e32 vcc, s42, v0
	s_nop 1
	v_cndmask_b32_e32 v0, v0, v1, vcc
	v_rsq_f32_e32 v0, v0
	s_nop 0
	v_mul_f32_e32 v1, 0x45800000, v0
	v_cndmask_b32_e32 v0, v0, v1, vcc
	v_mul_f32_e32 v0, v150, v0
	v_pk_mul_f32 v[186:187], v[16:17], v[0:1] op_sel_hi:[1,0]
	v_pk_mul_f32 v[2:3], v[18:19], v[0:1] op_sel_hi:[1,0]
	v_pk_mul_f32 v[4:5], v[20:21], v[0:1] op_sel_hi:[1,0]
	v_pk_mul_f32 v[6:7], v[22:23], v[0:1] op_sel_hi:[1,0]
	v_pk_mul_f32 v[8:9], v[24:25], v[0:1] op_sel_hi:[1,0]
	v_pk_mul_f32 v[10:11], v[26:27], v[0:1] op_sel_hi:[1,0]
	v_pk_mul_f32 v[12:13], v[28:29], v[0:1] op_sel_hi:[1,0]
	v_pk_mul_f32 v[0:1], v[30:31], v[0:1] op_sel_hi:[1,0]
	v_pk_mul_f32 v[12:13], v[174:175], v[12:13]
	v_pk_mul_f32 v[14:15], v[176:177], v[0:1]
	v_pk_mul_f32 v[10:11], v[172:173], v[10:11]
	v_pk_mul_f32 v[8:9], v[170:171], v[8:9]
	v_pk_mul_f32 v[6:7], v[168:169], v[6:7]
	v_pk_mul_f32 v[4:5], v[166:167], v[4:5]
	v_pk_mul_f32 v[2:3], v[164:165], v[2:3]
	v_pk_mul_f32 v[0:1], v[162:163], v[186:187]
	s_cbranch_execnz .LBB0_514

.LBB0_526:
	s_andn2_b64 vcc, exec, s[4:5]
	s_cbranch_vccnz .LBB0_533
	s_and_b64 vcc, exec, s[10:11]
	s_cbranch_vccnz .LBB0_633
	v_mul_f32_e32 v4, v129, v129
	v_fmac_f32_e32 v4, v128, v128
	v_fmac_f32_e32 v4, v130, v130
	v_fmac_f32_e32 v4, v131, v131
	v_fmac_f32_e32 v4, v132, v132
	v_fmac_f32_e32 v4, v133, v133
	v_fmac_f32_e32 v4, v134, v134
	v_fmac_f32_e32 v4, v135, v135
	v_pk_mul_f32 v[2:3], v[136:137], v[136:137]
	v_pk_mul_f32 v[0:1], v[138:139], v[138:139]
	v_add_f32_e32 v2, v2, v4
	v_add_f32_e32 v2, v3, v2
	v_add_f32_e32 v0, v0, v2
	v_add_f32_e32 v4, v1, v0
	v_pk_mul_f32 v[2:3], v[140:141], v[140:141]
	v_pk_mul_f32 v[0:1], v[142:143], v[142:143]
	v_add_f32_e32 v2, v2, v4
	v_add_f32_e32 v2, v3, v2
	v_add_f32_e32 v0, v0, v2
	v_add_f32_e32 v0, v1, v0
	v_mov_b32_e32 v1, v0
	s_nop 1
	v_permlane16_swap_b32_e32 v1, v0
	v_add_f32_e32 v0, v0, v1
	v_mov_b32_e32 v1, v0
	s_nop 1
	v_permlane32_swap_b32_e32 v1, v0
	v_add_f32_e32 v0, v0, v1
	v_mul_f32_e32 v1, v16, v16
	v_mul_f32_e32 v0, v1, v0
	v_fmamk_f32 v0, v0, 0x3c800000, v194
	v_mul_f32_e32 v1, 0x4b800000, v0
	v_cmp_gt_f32_e32 vcc, s42, v0
	s_nop 1
	v_cndmask_b32_e32 v0, v0, v1, vcc
	v_rsq_f32_e32 v0, v0
	s_nop 0
	v_mul_f32_e32 v1, 0x45800000, v0
	v_cndmask_b32_e32 v0, v0, v1, vcc
	v_mul_f32_e32 v0, v16, v0
	v_pk_mul_f32 v[18:19], v[128:129], v[0:1] op_sel_hi:[1,0]
	v_pk_mul_f32 v[2:3], v[130:131], v[0:1] op_sel_hi:[1,0]
	v_pk_mul_f32 v[4:5], v[132:133], v[0:1] op_sel_hi:[1,0]
	v_pk_mul_f32 v[6:7], v[134:135], v[0:1] op_sel_hi:[1,0]
	v_pk_mul_f32 v[8:9], v[136:137], v[0:1] op_sel_hi:[1,0]
	v_pk_mul_f32 v[10:11], v[138:139], v[0:1] op_sel_hi:[1,0]
	v_pk_mul_f32 v[12:13], v[140:141], v[0:1] op_sel_hi:[1,0]
	v_pk_mul_f32 v[0:1], v[142:143], v[0:1] op_sel_hi:[1,0]
	v_pk_mul_f32 v[12:13], v[174:175], v[12:13]
	v_pk_mul_f32 v[14:15], v[176:177], v[0:1]
	v_pk_mul_f32 v[10:11], v[172:173], v[10:11]
	v_pk_mul_f32 v[8:9], v[170:171], v[8:9]
	v_pk_mul_f32 v[6:7], v[168:169], v[6:7]
	v_pk_mul_f32 v[4:5], v[166:167], v[4:5]
	v_pk_mul_f32 v[2:3], v[164:165], v[2:3]
	v_pk_mul_f32 v[0:1], v[162:163], v[18:19]
	s_cbranch_execnz .LBB0_530

.LBB0_542:
	s_andn2_b64 vcc, exec, s[4:5]
	s_cbranch_vccnz .LBB0_549
	s_and_b64 vcc, exec, s[10:11]
	s_cbranch_vccnz .LBB0_634
	v_mul_f32_e32 v4, v113, v113
	v_fmac_f32_e32 v4, v112, v112
	v_fmac_f32_e32 v4, v114, v114
	v_fmac_f32_e32 v4, v115, v115
	v_fmac_f32_e32 v4, v116, v116
	v_fmac_f32_e32 v4, v117, v117
	v_fmac_f32_e32 v4, v118, v118
	v_fmac_f32_e32 v4, v119, v119
	v_pk_mul_f32 v[2:3], v[120:121], v[120:121]
	v_pk_mul_f32 v[0:1], v[122:123], v[122:123]
	v_add_f32_e32 v2, v2, v4
	v_add_f32_e32 v2, v3, v2
	v_add_f32_e32 v0, v0, v2
	v_add_f32_e32 v4, v1, v0
	v_pk_mul_f32 v[2:3], v[124:125], v[124:125]
	v_pk_mul_f32 v[0:1], v[126:127], v[126:127]
	v_add_f32_e32 v2, v2, v4
	v_add_f32_e32 v2, v3, v2
	v_add_f32_e32 v0, v0, v2
	v_add_f32_e32 v0, v1, v0
	v_mov_b32_e32 v1, v0
	s_nop 1
	v_permlane16_swap_b32_e32 v1, v0
	v_add_f32_e32 v0, v0, v1
	v_mov_b32_e32 v1, v0
	s_nop 1
	v_permlane32_swap_b32_e32 v1, v0
	v_add_f32_e32 v0, v0, v1
	v_mul_f32_e32 v1, v16, v16
	v_mul_f32_e32 v0, v1, v0
	v_fmamk_f32 v0, v0, 0x3c800000, v194
	v_mul_f32_e32 v1, 0x4b800000, v0
	v_cmp_gt_f32_e32 vcc, s42, v0
	s_nop 1
	v_cndmask_b32_e32 v0, v0, v1, vcc
	v_rsq_f32_e32 v0, v0
	s_nop 0
	v_mul_f32_e32 v1, 0x45800000, v0
	v_cndmask_b32_e32 v0, v0, v1, vcc
	v_mul_f32_e32 v0, v16, v0
	v_pk_mul_f32 v[18:19], v[112:113], v[0:1] op_sel_hi:[1,0]
	v_pk_mul_f32 v[2:3], v[114:115], v[0:1] op_sel_hi:[1,0]
	v_pk_mul_f32 v[4:5], v[116:117], v[0:1] op_sel_hi:[1,0]
	v_pk_mul_f32 v[6:7], v[118:119], v[0:1] op_sel_hi:[1,0]
	v_pk_mul_f32 v[8:9], v[120:121], v[0:1] op_sel_hi:[1,0]
	v_pk_mul_f32 v[10:11], v[122:123], v[0:1] op_sel_hi:[1,0]
	v_pk_mul_f32 v[12:13], v[124:125], v[0:1] op_sel_hi:[1,0]
	v_pk_mul_f32 v[0:1], v[126:127], v[0:1] op_sel_hi:[1,0]
	v_pk_mul_f32 v[12:13], v[174:175], v[12:13]
	v_pk_mul_f32 v[14:15], v[176:177], v[0:1]
	v_pk_mul_f32 v[10:11], v[172:173], v[10:11]
	v_pk_mul_f32 v[8:9], v[170:171], v[8:9]
	v_pk_mul_f32 v[6:7], v[168:169], v[6:7]
	v_pk_mul_f32 v[4:5], v[166:167], v[4:5]
	v_pk_mul_f32 v[2:3], v[164:165], v[2:3]
	v_pk_mul_f32 v[0:1], v[162:163], v[18:19]
	s_cbranch_execnz .LBB0_546

.LBB0_558:
	s_andn2_b64 vcc, exec, s[4:5]
	s_cbranch_vccnz .LBB0_565
	s_and_b64 vcc, exec, s[10:11]
	s_cbranch_vccnz .LBB0_635
	v_mul_f32_e32 v4, v97, v97
	v_fmac_f32_e32 v4, v96, v96
	v_fmac_f32_e32 v4, v98, v98
	v_fmac_f32_e32 v4, v99, v99
	v_fmac_f32_e32 v4, v100, v100
	v_fmac_f32_e32 v4, v101, v101
	v_fmac_f32_e32 v4, v102, v102
	v_fmac_f32_e32 v4, v103, v103
	v_pk_mul_f32 v[2:3], v[104:105], v[104:105]
	v_pk_mul_f32 v[0:1], v[106:107], v[106:107]
	v_add_f32_e32 v2, v2, v4
	v_add_f32_e32 v2, v3, v2
	v_add_f32_e32 v0, v0, v2
	v_add_f32_e32 v4, v1, v0
	v_pk_mul_f32 v[2:3], v[108:109], v[108:109]
	v_pk_mul_f32 v[0:1], v[110:111], v[110:111]
	v_add_f32_e32 v2, v2, v4
	v_add_f32_e32 v2, v3, v2
	v_add_f32_e32 v0, v0, v2
	v_add_f32_e32 v0, v1, v0
	v_mov_b32_e32 v1, v0
	s_nop 1
	v_permlane16_swap_b32_e32 v1, v0
	v_add_f32_e32 v0, v0, v1
	v_mov_b32_e32 v1, v0
	s_nop 1
	v_permlane32_swap_b32_e32 v1, v0
	v_add_f32_e32 v0, v0, v1
	v_mul_f32_e32 v1, v16, v16
	v_mul_f32_e32 v0, v1, v0
	v_fmamk_f32 v0, v0, 0x3c800000, v194
	v_mul_f32_e32 v1, 0x4b800000, v0
	v_cmp_gt_f32_e32 vcc, s42, v0
	s_nop 1
	v_cndmask_b32_e32 v0, v0, v1, vcc
	v_rsq_f32_e32 v0, v0
	s_nop 0
	v_mul_f32_e32 v1, 0x45800000, v0
	v_cndmask_b32_e32 v0, v0, v1, vcc
	v_mul_f32_e32 v0, v16, v0
	v_pk_mul_f32 v[18:19], v[96:97], v[0:1] op_sel_hi:[1,0]
	v_pk_mul_f32 v[2:3], v[98:99], v[0:1] op_sel_hi:[1,0]
	v_pk_mul_f32 v[4:5], v[100:101], v[0:1] op_sel_hi:[1,0]
	v_pk_mul_f32 v[6:7], v[102:103], v[0:1] op_sel_hi:[1,0]
	v_pk_mul_f32 v[8:9], v[104:105], v[0:1] op_sel_hi:[1,0]
	v_pk_mul_f32 v[10:11], v[106:107], v[0:1] op_sel_hi:[1,0]
	v_pk_mul_f32 v[12:13], v[108:109], v[0:1] op_sel_hi:[1,0]
	v_pk_mul_f32 v[0:1], v[110:111], v[0:1] op_sel_hi:[1,0]
	v_pk_mul_f32 v[12:13], v[174:175], v[12:13]
	v_pk_mul_f32 v[14:15], v[176:177], v[0:1]
	v_pk_mul_f32 v[10:11], v[172:173], v[10:11]
	v_pk_mul_f32 v[8:9], v[170:171], v[8:9]
	v_pk_mul_f32 v[6:7], v[168:169], v[6:7]
	v_pk_mul_f32 v[4:5], v[166:167], v[4:5]
	v_pk_mul_f32 v[2:3], v[164:165], v[2:3]
	v_pk_mul_f32 v[0:1], v[162:163], v[18:19]
	s_cbranch_execnz .LBB0_562

.LBB0_574:
	s_ashr_i32 s72, s76, 11
	s_mul_i32 s65, s65, s72
	s_add_i32 s72, s65, s63
	s_ashr_i32 s73, s72, 31
	s_lshl_b64 s[72:73], s[72:73], 18
	s_andn2_b64 vcc, exec, s[4:5]
	v_lshl_add_u64 v[96:97], v[180:181], 0, s[72:73]
	s_cbranch_vccnz .LBB0_581
	s_and_b64 vcc, exec, s[10:11]
	s_cbranch_vccnz .LBB0_636
	v_mul_f32_e32 v4, v81, v81
	v_fmac_f32_e32 v4, v80, v80
	v_fmac_f32_e32 v4, v82, v82
	v_fmac_f32_e32 v4, v83, v83
	v_fmac_f32_e32 v4, v84, v84
	v_fmac_f32_e32 v4, v85, v85
	v_fmac_f32_e32 v4, v86, v86
	v_fmac_f32_e32 v4, v87, v87
	v_pk_mul_f32 v[2:3], v[88:89], v[88:89]
	v_pk_mul_f32 v[0:1], v[90:91], v[90:91]
	v_add_f32_e32 v2, v2, v4
	v_add_f32_e32 v2, v3, v2
	v_add_f32_e32 v0, v0, v2
	v_add_f32_e32 v4, v1, v0
	v_pk_mul_f32 v[2:3], v[92:93], v[92:93]
	v_pk_mul_f32 v[0:1], v[94:95], v[94:95]
	v_add_f32_e32 v2, v2, v4
	v_add_f32_e32 v2, v3, v2
	v_add_f32_e32 v0, v0, v2
	v_add_f32_e32 v0, v1, v0
	v_mov_b32_e32 v1, v0
	s_nop 1
	v_permlane16_swap_b32_e32 v1, v0
	v_add_f32_e32 v0, v0, v1
	v_mov_b32_e32 v1, v0
	s_nop 1
	v_permlane32_swap_b32_e32 v1, v0
	v_add_f32_e32 v0, v0, v1
	v_mul_f32_e32 v1, v16, v16
	v_mul_f32_e32 v0, v1, v0
	v_fmamk_f32 v0, v0, 0x3c800000, v194
	v_mul_f32_e32 v1, 0x4b800000, v0
	v_cmp_gt_f32_e32 vcc, s42, v0
	s_nop 1
	v_cndmask_b32_e32 v0, v0, v1, vcc
	v_rsq_f32_e32 v0, v0
	s_nop 0
	v_mul_f32_e32 v1, 0x45800000, v0
	v_cndmask_b32_e32 v0, v0, v1, vcc
	v_mul_f32_e32 v0, v16, v0
	v_pk_mul_f32 v[18:19], v[80:81], v[0:1] op_sel_hi:[1,0]
	v_pk_mul_f32 v[2:3], v[82:83], v[0:1] op_sel_hi:[1,0]
	v_pk_mul_f32 v[4:5], v[84:85], v[0:1] op_sel_hi:[1,0]
	v_pk_mul_f32 v[6:7], v[86:87], v[0:1] op_sel_hi:[1,0]
	v_pk_mul_f32 v[8:9], v[88:89], v[0:1] op_sel_hi:[1,0]
	v_pk_mul_f32 v[10:11], v[90:91], v[0:1] op_sel_hi:[1,0]
	v_pk_mul_f32 v[12:13], v[92:93], v[0:1] op_sel_hi:[1,0]
	v_pk_mul_f32 v[0:1], v[94:95], v[0:1] op_sel_hi:[1,0]
	v_pk_mul_f32 v[12:13], v[174:175], v[12:13]
	v_pk_mul_f32 v[14:15], v[176:177], v[0:1]
	v_pk_mul_f32 v[10:11], v[172:173], v[10:11]
	v_pk_mul_f32 v[8:9], v[170:171], v[8:9]
	v_pk_mul_f32 v[6:7], v[168:169], v[6:7]
	v_pk_mul_f32 v[4:5], v[166:167], v[4:5]
	v_pk_mul_f32 v[2:3], v[164:165], v[2:3]
	v_pk_mul_f32 v[0:1], v[162:163], v[18:19]
	s_cbranch_execnz .LBB0_578

.LBB0_590:
	s_andn2_b64 vcc, exec, s[4:5]
	s_cbranch_vccnz .LBB0_597
	s_and_b64 vcc, exec, s[10:11]
	s_cbranch_vccnz .LBB0_637
	v_mul_f32_e32 v4, v65, v65
	v_fmac_f32_e32 v4, v64, v64
	v_fmac_f32_e32 v4, v66, v66
	v_fmac_f32_e32 v4, v67, v67
	v_fmac_f32_e32 v4, v68, v68
	v_fmac_f32_e32 v4, v69, v69
	v_fmac_f32_e32 v4, v70, v70
	v_fmac_f32_e32 v4, v71, v71
	v_pk_mul_f32 v[2:3], v[72:73], v[72:73]
	v_pk_mul_f32 v[0:1], v[74:75], v[74:75]
	v_add_f32_e32 v2, v2, v4
	v_add_f32_e32 v2, v3, v2
	v_add_f32_e32 v0, v0, v2
	v_add_f32_e32 v4, v1, v0
	v_pk_mul_f32 v[2:3], v[76:77], v[76:77]
	v_pk_mul_f32 v[0:1], v[78:79], v[78:79]
	v_add_f32_e32 v2, v2, v4
	v_add_f32_e32 v2, v3, v2
	v_add_f32_e32 v0, v0, v2
	v_add_f32_e32 v0, v1, v0
	v_mov_b32_e32 v1, v0
	s_nop 1
	v_permlane16_swap_b32_e32 v1, v0
	v_add_f32_e32 v0, v0, v1
	v_mov_b32_e32 v1, v0
	s_nop 1
	v_permlane32_swap_b32_e32 v1, v0
	v_add_f32_e32 v0, v0, v1
	v_mul_f32_e32 v1, v16, v16
	v_mul_f32_e32 v0, v1, v0
	v_fmamk_f32 v0, v0, 0x3c800000, v194
	v_mul_f32_e32 v1, 0x4b800000, v0
	v_cmp_gt_f32_e32 vcc, s42, v0
	s_nop 1
	v_cndmask_b32_e32 v0, v0, v1, vcc
	v_rsq_f32_e32 v0, v0
	s_nop 0
	v_mul_f32_e32 v1, 0x45800000, v0
	v_cndmask_b32_e32 v0, v0, v1, vcc
	v_mul_f32_e32 v0, v16, v0
	v_pk_mul_f32 v[18:19], v[64:65], v[0:1] op_sel_hi:[1,0]
	v_pk_mul_f32 v[2:3], v[66:67], v[0:1] op_sel_hi:[1,0]
	v_pk_mul_f32 v[4:5], v[68:69], v[0:1] op_sel_hi:[1,0]
	v_pk_mul_f32 v[6:7], v[70:71], v[0:1] op_sel_hi:[1,0]
	v_pk_mul_f32 v[8:9], v[72:73], v[0:1] op_sel_hi:[1,0]
	v_pk_mul_f32 v[10:11], v[74:75], v[0:1] op_sel_hi:[1,0]
	v_pk_mul_f32 v[12:13], v[76:77], v[0:1] op_sel_hi:[1,0]
	v_pk_mul_f32 v[0:1], v[78:79], v[0:1] op_sel_hi:[1,0]
	v_pk_mul_f32 v[12:13], v[174:175], v[12:13]
	v_pk_mul_f32 v[14:15], v[176:177], v[0:1]
	v_pk_mul_f32 v[10:11], v[172:173], v[10:11]
	v_pk_mul_f32 v[8:9], v[170:171], v[8:9]
	v_pk_mul_f32 v[6:7], v[168:169], v[6:7]
	v_pk_mul_f32 v[4:5], v[166:167], v[4:5]
	v_pk_mul_f32 v[2:3], v[164:165], v[2:3]
	v_pk_mul_f32 v[0:1], v[162:163], v[18:19]
	s_cbranch_execnz .LBB0_594

.LBB0_606:
	s_andn2_b64 vcc, exec, s[4:5]
	s_cbranch_vccnz .LBB0_613
	s_and_b64 vcc, exec, s[10:11]
	s_cbranch_vccnz .LBB0_638
	v_mul_f32_e32 v4, v49, v49
	v_fmac_f32_e32 v4, v48, v48
	v_fmac_f32_e32 v4, v50, v50
	v_fmac_f32_e32 v4, v51, v51
	v_fmac_f32_e32 v4, v52, v52
	v_fmac_f32_e32 v4, v53, v53
	v_fmac_f32_e32 v4, v54, v54
	v_fmac_f32_e32 v4, v55, v55
	v_pk_mul_f32 v[2:3], v[56:57], v[56:57]
	v_pk_mul_f32 v[0:1], v[58:59], v[58:59]
	v_add_f32_e32 v2, v2, v4
	v_add_f32_e32 v2, v3, v2
	v_add_f32_e32 v0, v0, v2
	v_add_f32_e32 v4, v1, v0
	v_pk_mul_f32 v[2:3], v[60:61], v[60:61]
	v_pk_mul_f32 v[0:1], v[62:63], v[62:63]
	v_add_f32_e32 v2, v2, v4
	v_add_f32_e32 v2, v3, v2
	v_add_f32_e32 v0, v0, v2
	v_add_f32_e32 v0, v1, v0
	v_mov_b32_e32 v1, v0
	s_nop 1
	v_permlane16_swap_b32_e32 v1, v0
	v_add_f32_e32 v0, v0, v1
	v_mov_b32_e32 v1, v0
	s_nop 1
	v_permlane32_swap_b32_e32 v1, v0
	v_add_f32_e32 v0, v0, v1
	v_mul_f32_e32 v1, v16, v16
	v_mul_f32_e32 v0, v1, v0
	v_fmamk_f32 v0, v0, 0x3c800000, v194
	v_mul_f32_e32 v1, 0x4b800000, v0
	v_cmp_gt_f32_e32 vcc, s42, v0
	s_nop 1
	v_cndmask_b32_e32 v0, v0, v1, vcc
	v_rsq_f32_e32 v0, v0
	s_nop 0
	v_mul_f32_e32 v1, 0x45800000, v0
	v_cndmask_b32_e32 v0, v0, v1, vcc
	v_mul_f32_e32 v0, v16, v0
	v_pk_mul_f32 v[18:19], v[48:49], v[0:1] op_sel_hi:[1,0]
	v_pk_mul_f32 v[2:3], v[50:51], v[0:1] op_sel_hi:[1,0]
	v_pk_mul_f32 v[4:5], v[52:53], v[0:1] op_sel_hi:[1,0]
	v_pk_mul_f32 v[6:7], v[54:55], v[0:1] op_sel_hi:[1,0]
	v_pk_mul_f32 v[8:9], v[56:57], v[0:1] op_sel_hi:[1,0]
	v_pk_mul_f32 v[10:11], v[58:59], v[0:1] op_sel_hi:[1,0]
	v_pk_mul_f32 v[12:13], v[60:61], v[0:1] op_sel_hi:[1,0]
	v_pk_mul_f32 v[0:1], v[62:63], v[0:1] op_sel_hi:[1,0]
	v_pk_mul_f32 v[12:13], v[174:175], v[12:13]
	v_pk_mul_f32 v[14:15], v[176:177], v[0:1]
	v_pk_mul_f32 v[10:11], v[172:173], v[10:11]
	v_pk_mul_f32 v[8:9], v[170:171], v[8:9]
	v_pk_mul_f32 v[6:7], v[168:169], v[6:7]
	v_pk_mul_f32 v[4:5], v[166:167], v[4:5]
	v_pk_mul_f32 v[2:3], v[164:165], v[2:3]
	v_pk_mul_f32 v[0:1], v[162:163], v[18:19]
	s_cbranch_execnz .LBB0_610

.LBB0_622:
	s_andn2_b64 vcc, exec, s[4:5]
	s_cbranch_vccnz .LBB0_629
	s_and_b64 vcc, exec, s[10:11]
	s_cbranch_vccnz .LBB0_639
	v_mul_f32_e32 v4, v37, v37
	v_fmac_f32_e32 v4, v36, v36
	v_fmac_f32_e32 v4, v38, v38
	v_fmac_f32_e32 v4, v39, v39
	v_fmac_f32_e32 v4, v40, v40
	v_fmac_f32_e32 v4, v41, v41
	v_fmac_f32_e32 v4, v42, v42
	v_fmac_f32_e32 v4, v43, v43
	v_pk_mul_f32 v[2:3], v[44:45], v[44:45]
	v_pk_mul_f32 v[0:1], v[46:47], v[46:47]
	v_add_f32_e32 v2, v2, v4
	v_add_f32_e32 v2, v3, v2
	v_add_f32_e32 v0, v0, v2
	v_add_f32_e32 v4, v1, v0
	v_pk_mul_f32 v[2:3], v[32:33], v[32:33]
	v_pk_mul_f32 v[0:1], v[34:35], v[34:35]
	v_add_f32_e32 v2, v2, v4
	v_add_f32_e32 v2, v3, v2
	v_add_f32_e32 v0, v0, v2
	v_add_f32_e32 v0, v1, v0
	v_mov_b32_e32 v1, v0
	s_nop 1
	v_permlane16_swap_b32_e32 v1, v0
	v_add_f32_e32 v0, v0, v1
	v_mov_b32_e32 v1, v0
	s_nop 1
	v_permlane32_swap_b32_e32 v1, v0
	v_add_f32_e32 v0, v0, v1
	v_mul_f32_e32 v1, v16, v16
	v_mul_f32_e32 v0, v1, v0
	v_fmamk_f32 v0, v0, 0x3c800000, v194
	v_mul_f32_e32 v1, 0x4b800000, v0
	v_cmp_gt_f32_e32 vcc, s42, v0
	s_nop 1
	v_cndmask_b32_e32 v0, v0, v1, vcc
	v_rsq_f32_e32 v0, v0
	s_nop 0
	v_mul_f32_e32 v1, 0x45800000, v0
	v_cndmask_b32_e32 v0, v0, v1, vcc
	v_mul_f32_e32 v0, v16, v0
	v_pk_mul_f32 v[18:19], v[36:37], v[0:1] op_sel_hi:[1,0]
	v_pk_mul_f32 v[2:3], v[38:39], v[0:1] op_sel_hi:[1,0]
	v_pk_mul_f32 v[4:5], v[40:41], v[0:1] op_sel_hi:[1,0]
	v_pk_mul_f32 v[6:7], v[42:43], v[0:1] op_sel_hi:[1,0]
	v_pk_mul_f32 v[8:9], v[44:45], v[0:1] op_sel_hi:[1,0]
	v_pk_mul_f32 v[10:11], v[46:47], v[0:1] op_sel_hi:[1,0]
	v_pk_mul_f32 v[12:13], v[32:33], v[0:1] op_sel_hi:[1,0]
	v_pk_mul_f32 v[0:1], v[34:35], v[0:1] op_sel_hi:[1,0]
	v_pk_mul_f32 v[12:13], v[174:175], v[12:13]
	v_pk_mul_f32 v[14:15], v[176:177], v[0:1]
	v_pk_mul_f32 v[10:11], v[172:173], v[10:11]
	v_pk_mul_f32 v[8:9], v[170:171], v[8:9]
	v_pk_mul_f32 v[6:7], v[168:169], v[6:7]
	v_pk_mul_f32 v[4:5], v[166:167], v[4:5]
	v_pk_mul_f32 v[2:3], v[164:165], v[2:3]
	v_pk_mul_f32 v[0:1], v[162:163], v[18:19]
	s_cbranch_execnz .LBB0_626
